# rmsnorm row loops of P0 (norm1), P6 (norm2) and P11 (final norm): gain vectors loaded once before the loop instead of 8 serialized load+wait per row; next row's loads stay in flight during the current
# speedup vs baseline: 1.0131x; 1.0027x over previous
; __device__ __forceinline__ unsigned cvtpk(float lo, float hi) { return pg8::cvt_pk_bf16(lo, hi); }
; __device__ __forceinline__ void rms_load(const float* xrow, int lane, f32x4 (&v)[8]) {
;     const f32x4* xr = (const f32x4*)xrow + lane;
; #pragma unroll
;     for (int j = 0; j < 8; ++j) v[j] = xr[64 * j];
; }
; __device__ __forceinline__ float rms_rstd(const f32x4 (&v)[8]) {
;     float s = 0.f;
; #pragma unroll
;     for (int j = 0; j < 8; ++j) s += (v[j].x * v[j].x + v[j].y * v[j].y) + (v[j].z * v[j].z + v[j].w * v[j].w);
;     return 1.0f / sqrtf(wave_sum(s) * (1.f / DM) + EPS);
; }
; __device__ __forceinline__ void rms_store_bf16(const f32x4 (&v)[8], const float* g, bf16* orow, int lane) {
;     const float rstd = rms_rstd(v); const f32x4* gr = (const f32x4*)g + lane; v2u* o8 = (v2u*)orow + lane;
; #pragma unroll
;     for (int j = 0; j < 8; ++j) { const f32x4 gg = gr[64 * j]; v2u w; w.x = cvtpk(v[j].x * rstd * gg.x, v[j].y * rstd * gg.y); w.y = cvtpk(v[j].z * rstd * gg.z, v[j].w * rstd * gg.w); o8[64 * j] = w; }
; }
; __global__ void __launch_bounds__(512, 2) fwd_megakernel(Args args) {
;     ...
;         {
;             int m = gw; f32x4 cur[8];
;             if (m < NTOK) rms_load(m < 8192 ? args.in[0] + (size_t)m * DM : args.in[1] + (size_t)(m - 8192) * DM, lane, cur);
;             for (; m < NTOK; m += NGW) { const int mn = m + NGW; f32x4 nxt[8];
;                 if (mn < NTOK) rms_load(mn < 8192 ? args.in[0] + (size_t)mn * DM : args.in[1] + (size_t)(mn - 8192) * DM, lane, nxt);
;                 rms_store_bf16(cur, args.in[3], XN + (size_t)m * DM, lane);
; #pragma unroll
;                 for (int j = 0; j < 8; ++j) cur[j] = nxt[j]; }
;         }
.LBB0_35:
	s_cmpk_lt_i32 s54, 0x6000
	s_cbranch_scc0 .LBB0_40
	s_add_i32 s0, s54, 0xffffe000
	s_ashr_i32 s55, s54, 31
	s_cmpk_lt_i32 s54, 0x2000
	s_cselect_b32 s1, s55, 0
	s_cselect_b32 s0, s54, s0
	s_cselect_b32 s4, s13, s15
	s_cselect_b32 s5, s12, s14
	s_lshl_b64 s[0:1], s[0:1], 13
	s_add_u32 s0, s5, s0
	v_mov_b32_e32 v69, 0
	s_addc_u32 s1, s4, s1
	v_mov_b32_e32 v65, v69
	v_lshl_add_u64 v[0:1], s[0:1], 0, v[64:65]
	global_load_dwordx4 v[60:63], v64, s[0:1]
	global_load_dwordx4 v[56:59], v64, s[0:1] offset:1024
	global_load_dwordx4 v[52:55], v64, s[0:1] offset:2048
	global_load_dwordx4 v[48:51], v64, s[0:1] offset:3072
	s_movk_i32 s0, 0x1000
	v_add_co_u32_e32 v0, vcc, s0, v0
	v_lshl_add_u64 v[70:71], s[18:19], 0, v[64:65]
	s_nop 0
	v_addc_co_u32_e32 v1, vcc, 0, v1, vcc
	global_load_dwordx4 v[44:47], v[0:1], off
	global_load_dwordx4 v[40:43], v[0:1], off offset:1024
	global_load_dwordx4 v[36:39], v[0:1], off offset:2048
	s_nop 0
	global_load_dwordx4 v[0:3], v[0:1], off offset:3072
	s_mov_b64 s[0:1], 0x1000
	v_lshl_add_u64 v[72:73], v[70:71], 0, s[0:1]
	s_mov_b64 s[0:1], 0x1400
	v_lshl_add_u64 v[74:75], v[70:71], 0, s[0:1]
	s_mov_b64 s[0:1], 0x1800
	v_lshl_add_u64 v[76:77], v[70:71], 0, s[0:1]
	s_mov_b64 s[0:1], 0x1c00
	v_lshl_add_u64 v[78:79], v[70:71], 0, s[0:1]
	s_lshl_b64 s[0:1], s[54:55], 12
	s_add_u32 s0, s50, s0
	v_mov_b32_e32 v67, v69
	s_addc_u32 s1, s51, s1
	v_lshl_add_u64 v[6:7], s[0:1], 0, v[66:67]
	s_mov_b64 s[0:1], 0x5c00e00
	s_ashr_i32 s53, s52, 31
	s_add_i32 s8, s54, s52
	v_lshl_add_u64 v[80:81], v[6:7], 0, s[0:1]
	s_lshl_b64 s[0:1], s[52:53], 12
	s_ashr_i32 s9, s8, 31
	v_lshlrev_b32_e32 v68, 4, v4
	v_mov_b32_e32 v65, 0x358637bd
	s_mov_b32 s10, 0xf800000
	v_mov_b32_e32 v67, 0x260
	s_mov_b32 s11, s54
	global_load_dwordx4 v[100:103], v[70:71], off
	global_load_dwordx4 v[104:107], v[70:71], off offset:1024
	global_load_dwordx4 v[108:111], v[70:71], off offset:2048
	global_load_dwordx4 v[112:115], v[70:71], off offset:3072
	global_load_dwordx4 v[116:119], v[72:73], off
	global_load_dwordx4 v[120:123], v[74:75], off
	global_load_dwordx4 v[124:127], v[76:77], off
	global_load_dwordx4 v[128:131], v[78:79], off
	s_branch .LBB0_38

; __device__ __forceinline__ unsigned cvtpk(float lo, float hi) { return pg8::cvt_pk_bf16(lo, hi); }
; __device__ __forceinline__ void rms_load(const float* xrow, int lane, f32x4 (&v)[8]) {
;     const f32x4* xr = (const f32x4*)xrow + lane;
; #pragma unroll
;     for (int j = 0; j < 8; ++j) v[j] = xr[64 * j];
; }
; __device__ __forceinline__ float rms_rstd(const f32x4 (&v)[8]) {
;     float s = 0.f;
; #pragma unroll
;     for (int j = 0; j < 8; ++j) s += (v[j].x * v[j].x + v[j].y * v[j].y) + (v[j].z * v[j].z + v[j].w * v[j].w);
;     return 1.0f / sqrtf(wave_sum(s) * (1.f / DM) + EPS);
; }
; __device__ __forceinline__ void rms_store_bf16(const f32x4 (&v)[8], const float* g, bf16* orow, int lane) {
;     const float rstd = rms_rstd(v); const f32x4* gr = (const f32x4*)g + lane; v2u* o8 = (v2u*)orow + lane;
; #pragma unroll
;     for (int j = 0; j < 8; ++j) { const f32x4 gg = gr[64 * j]; v2u w; w.x = cvtpk(v[j].x * rstd * gg.x, v[j].y * rstd * gg.y); w.y = cvtpk(v[j].z * rstd * gg.z, v[j].w * rstd * gg.w); o8[64 * j] = w; }
; }
; __global__ void __launch_bounds__(512, 2) fwd_megakernel(Args args) {
;     ...
;         {
;             int m = gw; f32x4 cur[8];
;             if (m < NTOK) rms_load(m < 8192 ? args.in[0] + (size_t)m * DM : args.in[1] + (size_t)(m - 8192) * DM, lane, cur);
;             for (; m < NTOK; m += NGW) { const int mn = m + NGW; f32x4 nxt[8];
;                 if (mn < NTOK) rms_load(mn < 8192 ? args.in[0] + (size_t)mn * DM : args.in[1] + (size_t)(mn - 8192) * DM, lane, nxt);
;                 rms_store_bf16(cur, args.in[3], XN + (size_t)m * DM, lane);
; #pragma unroll
;                 for (int j = 0; j < 8; ++j) cur[j] = nxt[j]; }
;         }
.Lp0n_body:
	v_pk_mul_f32 v[94:95], v[60:61], v[60:61]
	v_pk_mul_f32 v[96:97], v[56:57], v[56:57]
	v_pk_mul_f32 v[90:91], v[62:63], v[62:63]
	v_pk_mul_f32 v[92:93], v[58:59], v[58:59]
	v_mov_b32_e32 v98, v94
	v_mov_b32_e32 v99, v96
	v_mov_b32_e32 v96, v95
	v_pk_mul_f32 v[86:87], v[54:55], v[54:55]
	v_pk_mul_f32 v[88:89], v[52:53], v[52:53]
	v_pk_add_f32 v[94:95], v[98:99], v[96:97]
	v_mov_b32_e32 v96, v90
	v_mov_b32_e32 v97, v92
	v_mov_b32_e32 v92, v91
	v_pk_add_f32 v[90:91], v[96:97], v[92:93]
	v_pk_mov_b32 v[92:93], v[88:89], v[86:87] op_sel:[1,0]
	v_mov_b32_e32 v89, v87
	v_pk_add_f32 v[86:87], v[92:93], v[88:89]
	v_pk_add_f32 v[90:91], v[94:95], v[90:91]
	v_pk_add_f32 v[86:87], v[86:87], v[86:87] op_sel_hi:[0,1]
	v_mul_f32_e32 v86, v48, v48
	v_pk_fma_f32 v[88:89], v[48:49], v[48:49], v[86:87] op_sel_hi:[1,1,0]
	v_mul_f32_e32 v86, v50, v50
	v_pk_add_f32 v[90:91], v[90:91], v[90:91] op_sel_hi:[0,1]
	v_pk_fma_f32 v[92:93], v[50:51], v[50:51], v[86:87] op_sel_hi:[1,1,0]
	v_mul_f32_e32 v88, v44, v44
	v_mul_f32_e32 v92, v45, v45
	v_mul_f32_e32 v86, v46, v46
	v_mul_f32_e32 v90, v47, v47
	v_pk_mul_f32 v[82:83], v[42:43], v[42:43]
	v_pk_mul_f32 v[84:85], v[40:41], v[40:41]
	v_pk_add_f32 v[88:89], v[88:89], v[92:93]
	v_pk_add_f32 v[86:87], v[86:87], v[90:91]
	s_add_i32 s11, s11, s52
	v_pk_add_f32 v[86:87], v[88:89], v[86:87]
	v_pk_mov_b32 v[88:89], v[84:85], v[82:83] op_sel:[1,0]
	v_mov_b32_e32 v85, v83
	v_pk_add_f32 v[82:83], v[88:89], v[84:85]
	v_pk_add_f32 v[86:87], v[86:87], v[86:87] op_sel_hi:[0,1]
	v_pk_add_f32 v[88:89], v[82:83], v[82:83] op_sel_hi:[0,1]
	v_mul_f32_e32 v82, v36, v36
	v_pk_fma_f32 v[90:91], v[36:37], v[36:37], v[82:83] op_sel_hi:[1,1,0]
	v_mul_f32_e32 v82, v38, v38
	v_pk_fma_f32 v[92:93], v[38:39], v[38:39], v[82:83] op_sel_hi:[1,1,0]
	v_mul_f32_e32 v90, v0, v0
	v_mul_f32_e32 v92, v1, v1
	v_mul_f32_e32 v88, v2, v2
	v_mul_f32_e32 v86, v3, v3
	v_pk_add_f32 v[90:91], v[90:91], v[92:93]
	v_pk_add_f32 v[86:87], v[88:89], v[86:87]
	s_add_u32 s8, s8, s52
	v_pk_add_f32 v[86:87], v[90:91], v[86:87]
	s_addc_u32 s9, s9, s53
	v_add_f32_e32 v86, v86, v87
	ds_bpermute_b32 v87, v246, v86
	s_cmpk_lt_i32 s11, 0x6000
	s_waitcnt lgkmcnt(0)
	v_add_f32_e32 v86, v86, v87
	ds_bpermute_b32 v87, v247, v86
	s_waitcnt lgkmcnt(0)
	v_add_f32_e32 v86, v86, v87
	ds_bpermute_b32 v87, v248, v86
	s_waitcnt lgkmcnt(0)
	v_add_f32_e32 v86, v86, v87
	ds_bpermute_b32 v87, v249, v86
	s_waitcnt lgkmcnt(0)
	v_add_f32_e32 v86, v86, v87
	ds_bpermute_b32 v87, v250, v86
	s_waitcnt lgkmcnt(0)
	v_add_f32_e32 v86, v86, v87
	ds_bpermute_b32 v87, v251, v86
	s_waitcnt lgkmcnt(0)
	v_add_f32_e32 v86, v86, v87
	v_fmamk_f32 v86, v86, 0x3a000000, v65
	v_mul_f32_e32 v87, 0x4f800000, v86
	v_cmp_gt_f32_e32 vcc, s10, v86
	s_nop 1
	v_cndmask_b32_e32 v86, v86, v87, vcc
	v_sqrt_f32_e32 v87, v86
	s_nop 0
	v_add_u32_e32 v88, -1, v87
	v_fma_f32 v89, -v88, v87, v86
	v_cmp_ge_f32_e64 s[4:5], 0, v89
	v_add_u32_e32 v89, 1, v87
	s_nop 0
	v_cndmask_b32_e64 v88, v87, v88, s[4:5]
	v_fma_f32 v87, -v89, v87, v86
	v_cmp_lt_f32_e64 s[4:5], 0, v87
	s_nop 1
	v_cndmask_b32_e64 v87, v88, v89, s[4:5]
	v_mul_f32_e32 v88, 0x37800000, v87
	v_cndmask_b32_e32 v87, v87, v88, vcc
	v_cmp_class_f32_e32 vcc, v86, v67
	s_nop 1
	v_cndmask_b32_e32 v86, v87, v86, vcc
	v_div_scale_f32 v87, s[4:5], v86, v86, 1.0
	v_rcp_f32_e32 v88, v87
	s_nop 0
	v_fma_f32 v89, -v87, v88, 1.0
	v_fmac_f32_e32 v88, v89, v88
	v_div_scale_f32 v89, vcc, 1.0, v86, 1.0
	v_mul_f32_e32 v90, v89, v88
	v_fma_f32 v91, -v87, v90, v89
	v_fmac_f32_e32 v90, v91, v88
	v_fma_f32 v87, -v87, v90, v89
	v_div_fmas_f32 v87, v87, v88, v90
	v_div_fixup_f32 v86, v87, v86, 1.0
	v_pk_mul_f32 v[60:61], v[60:61], v[86:87] op_sel_hi:[1,0]
	v_pk_mul_f32 v[62:63], v[62:63], v[86:87] op_sel_hi:[1,0]
	v_pk_mul_f32 v[60:61], v[100:101], v[60:61]
	v_pk_mul_f32 v[62:63], v[102:103], v[62:63]
	v_cvt_pk_bf16_f32 v60, v60, v61
	v_cvt_pk_bf16_f32 v61, v62, v63
	global_store_dwordx2 v[80:81], v[60:61], off offset:-3584
	v_pk_mul_f32 v[56:57], v[56:57], v[86:87] op_sel_hi:[1,0]
	v_pk_mul_f32 v[58:59], v[58:59], v[86:87] op_sel_hi:[1,0]
	v_pk_mul_f32 v[52:53], v[52:53], v[86:87] op_sel_hi:[1,0]
	v_pk_mul_f32 v[54:55], v[54:55], v[86:87] op_sel_hi:[1,0]
	v_pk_mul_f32 v[48:49], v[48:49], v[86:87] op_sel_hi:[1,0]
	v_pk_mul_f32 v[50:51], v[50:51], v[86:87] op_sel_hi:[1,0]
	v_pk_mul_f32 v[44:45], v[44:45], v[86:87] op_sel_hi:[1,0]
	v_pk_mul_f32 v[46:47], v[46:47], v[86:87] op_sel_hi:[1,0]
	v_pk_mul_f32 v[40:41], v[40:41], v[86:87] op_sel_hi:[1,0]
	v_pk_mul_f32 v[42:43], v[42:43], v[86:87] op_sel_hi:[1,0]
	v_pk_mul_f32 v[36:37], v[36:37], v[86:87] op_sel_hi:[1,0]
	v_pk_mul_f32 v[38:39], v[38:39], v[86:87] op_sel_hi:[1,0]
	v_pk_mul_f32 v[88:89], v[0:1], v[86:87] op_sel_hi:[1,0]
	v_pk_mul_f32 v[86:87], v[2:3], v[86:87] op_sel_hi:[1,0]
	s_waitcnt vmcnt(0)
; __device__ __forceinline__ unsigned cvtpk(float lo, float hi) { return pg8::cvt_pk_bf16(lo, hi); }
; __device__ __forceinline__ void rms_load(const float* xrow, int lane, f32x4 (&v)[8]) {
;     const f32x4* xr = (const f32x4*)xrow + lane;
; #pragma unroll
;     for (int j = 0; j < 8; ++j) v[j] = xr[64 * j];
; }
; __device__ __forceinline__ float rms_rstd(const f32x4 (&v)[8]) {
;     float s = 0.f;
; #pragma unroll
;     for (int j = 0; j < 8; ++j) s += (v[j].x * v[j].x + v[j].y * v[j].y) + (v[j].z * v[j].z + v[j].w * v[j].w);
;     return 1.0f / sqrtf(wave_sum(s) * (1.f / DM) + EPS);
; }
; __device__ __forceinline__ void rms_store_bf16(const f32x4 (&v)[8], const float* g, bf16* orow, int lane) {
;     const float rstd = rms_rstd(v); const f32x4* gr = (const f32x4*)g + lane; v2u* o8 = (v2u*)orow + lane;
; #pragma unroll
;     for (int j = 0; j < 8; ++j) { const f32x4 gg = gr[64 * j]; v2u w; w.x = cvtpk(v[j].x * rstd * gg.x, v[j].y * rstd * gg.y); w.y = cvtpk(v[j].z * rstd * gg.z, v[j].w * rstd * gg.w); o8[64 * j] = w; }
; }
; __global__ void __launch_bounds__(512, 2) fwd_megakernel(Args args) {
;     ...
;         {
;             int m = gw; f32x4 cur[8];
;             if (m < NTOK) rms_load(m < 8192 ? args.in[0] + (size_t)m * DM : args.in[1] + (size_t)(m - 8192) * DM, lane, cur);
;             for (; m < NTOK; m += NGW) { const int mn = m + NGW; f32x4 nxt[8];
;                 if (mn < NTOK) rms_load(mn < 8192 ? args.in[0] + (size_t)mn * DM : args.in[1] + (size_t)(mn - 8192) * DM, lane, nxt);
;                 rms_store_bf16(cur, args.in[3], XN + (size_t)m * DM, lane);
; #pragma unroll
;                 for (int j = 0; j < 8; ++j) cur[j] = nxt[j]; }
;         }
;         for (int m = NTOK + gw; m < MP; m += NGW) {
;             bf16* orow = XN + (size_t)m * DM;
;             if (m < NTOK + NMETA) rms_row_to_bf16(args.in[2] + (size_t)(m - NTOK) * DM, args.in[3], orow, lane);
;             else { v4u z = {0u, 0u, 0u, 0u};
; #pragma unroll
;                 for (int j = 0; j < 4; ++j) ((v4u*)orow)[lane + 64 * j] = z; }
;         }
	v_mov_b32_e32 v0, v20
	v_mov_b32_e32 v1, v21
	v_mov_b32_e32 v2, v22
	v_mov_b32_e32 v3, v23
	v_pk_mul_f32 v[56:57], v[104:105], v[56:57]
	v_pk_mul_f32 v[58:59], v[106:107], v[58:59]
	v_cvt_pk_bf16_f32 v56, v56, v57
	v_cvt_pk_bf16_f32 v57, v58, v59
	global_store_dwordx2 v[80:81], v[56:57], off offset:-3072
	v_mov_b32_e32 v60, v16
	v_mov_b32_e32 v61, v17
	v_mov_b32_e32 v62, v18
	v_mov_b32_e32 v63, v19
	v_pk_mul_f32 v[52:53], v[108:109], v[52:53]
	v_pk_mul_f32 v[54:55], v[110:111], v[54:55]
	v_cvt_pk_bf16_f32 v52, v52, v53
	v_cvt_pk_bf16_f32 v53, v54, v55
	global_store_dwordx2 v[80:81], v[52:53], off offset:-2560
	v_mov_b32_e32 v56, v12
	v_mov_b32_e32 v57, v13
	v_mov_b32_e32 v58, v14
	v_mov_b32_e32 v59, v15
	v_pk_mul_f32 v[48:49], v[48:49], v[112:113]
	v_pk_mul_f32 v[50:51], v[50:51], v[114:115]
	v_cvt_pk_bf16_f32 v48, v48, v49
	v_cvt_pk_bf16_f32 v49, v50, v51
	global_store_dwordx2 v[80:81], v[48:49], off offset:-2048
	v_mov_b32_e32 v52, v8
	v_mov_b32_e32 v53, v9
	v_mov_b32_e32 v54, v10
	v_mov_b32_e32 v55, v11
	v_pk_mul_f32 v[44:45], v[44:45], v[116:117]
	v_pk_mul_f32 v[46:47], v[46:47], v[118:119]
	v_cvt_pk_bf16_f32 v44, v44, v45
	v_cvt_pk_bf16_f32 v45, v46, v47
	global_store_dwordx2 v[80:81], v[44:45], off offset:-1536
	v_mov_b32_e32 v48, v4
	v_mov_b32_e32 v49, v5
	v_mov_b32_e32 v50, v6
	v_mov_b32_e32 v51, v7
	v_pk_mul_f32 v[40:41], v[40:41], v[120:121]
	v_pk_mul_f32 v[42:43], v[42:43], v[122:123]
	v_cvt_pk_bf16_f32 v40, v40, v41
	v_cvt_pk_bf16_f32 v41, v42, v43
	global_store_dwordx2 v[80:81], v[40:41], off offset:-1024
	v_mov_b32_e32 v44, v32
	v_mov_b32_e32 v45, v33
	v_mov_b32_e32 v46, v34
	v_mov_b32_e32 v47, v35
	v_pk_mul_f32 v[36:37], v[36:37], v[124:125]
	v_pk_mul_f32 v[38:39], v[38:39], v[126:127]
	v_cvt_pk_bf16_f32 v36, v36, v37
	v_cvt_pk_bf16_f32 v37, v38, v39
	global_store_dwordx2 v[80:81], v[36:37], off offset:-512
	v_mov_b32_e32 v40, v28
	v_mov_b32_e32 v41, v29
	v_mov_b32_e32 v42, v30
	v_mov_b32_e32 v43, v31
	v_mov_b32_e32 v36, v24
	v_mov_b32_e32 v37, v25
	v_mov_b32_e32 v38, v26
	v_mov_b32_e32 v39, v27
	v_pk_mul_f32 v[82:83], v[88:89], v[128:129]
	v_pk_mul_f32 v[84:85], v[86:87], v[130:131]
	v_cvt_pk_bf16_f32 v82, v82, v83
	v_cvt_pk_bf16_f32 v83, v84, v85
	global_store_dwordx2 v[80:81], v[82:83], off
	v_lshl_add_u64 v[80:81], v[80:81], 0, s[0:1]
	s_cbranch_scc0 .LBB0_40
.LBB0_38:
	s_cmpk_gt_i32 s8, 0x5fff
	s_cbranch_scc1 .Lp0n_nonext
	s_add_i32 s4, s8, 0xffffe000
	s_cmpk_lt_i32 s8, 0x2000
	s_cselect_b32 s5, s9, 0
	s_cselect_b32 s4, s8, s4
	s_cselect_b32 s20, s13, s15
	s_cselect_b32 s21, s12, s14
	s_lshl_b64 s[4:5], s[4:5], 13
	s_add_u32 s4, s21, s4
	s_addc_u32 s5, s20, s5
	v_lshl_add_u64 v[20:21], s[4:5], 0, v[68:69]
	v_add_co_u32_e32 v20, vcc, 0x1000, v20
	global_load_dwordx4 v[16:19], v68, s[4:5]
	global_load_dwordx4 v[12:15], v68, s[4:5] offset:1024
	global_load_dwordx4 v[8:11], v68, s[4:5] offset:2048
	global_load_dwordx4 v[4:7], v68, s[4:5] offset:3072
	v_addc_co_u32_e32 v21, vcc, 0, v21, vcc
	global_load_dwordx4 v[32:35], v[20:21], off
	global_load_dwordx4 v[28:31], v[20:21], off offset:1024
	global_load_dwordx4 v[24:27], v[20:21], off offset:2048
	s_nop 0
	global_load_dwordx4 v[20:23], v[20:21], off offset:3072
	s_branch .LBB0_37
.Lp0n_nonext:
	s_waitcnt vmcnt(0)
	s_branch .Lp0n_body
.LBB0_40:
	s_cmpk_gt_i32 s54, 0xff
	s_cbranch_scc1 .LBB0_47
	v_mov_b32_e32 v65, 0
	v_lshl_add_u64 v[34:35], s[18:19], 0, v[64:65]
	s_mov_b64 s[0:1], 0x1000
	v_lshl_add_u64 v[36:37], v[34:35], 0, s[0:1]
	s_mov_b64 s[0:1], 0x1400
	v_lshl_add_u64 v[38:39], v[34:35], 0, s[0:1]
	s_mov_b64 s[0:1], 0x1800
	v_lshl_add_u64 v[40:41], v[34:35], 0, s[0:1]
	s_mov_b64 s[0:1], 0x1c00
	s_ashr_i32 s55, s54, 31
	v_lshl_add_u64 v[42:43], v[34:35], 0, s[0:1]
	s_lshl_b64 s[0:1], s[54:55], 12
	s_add_u32 s0, s50, s0
	s_addc_u32 s1, s51, s1
	s_add_u32 s0, s0, 0x6000000
	s_addc_u32 s1, s1, 0
	s_ashr_i32 s53, s52, 31
	v_lshl_add_u64 v[32:33], s[16:17], 0, v[64:65]
	v_mov_b32_e32 v67, v65
	s_lshl_b64 s[16:17], s[52:53], 12
	s_mov_b32 s20, 0x5c00000
	s_mov_b32 s8, 0
	s_movk_i32 s21, 0x1000
	v_mov_b32_e32 v44, 0x358637bd
	s_mov_b32 s38, 0xf800000
	v_mov_b32_e32 v45, 0x260
	s_mov_b32 s18, s54
	s_branch .LBB0_43

; __device__ __forceinline__ float rms_rstd(const f32x4 (&v)[8]) {
;     float s = 0.f;
; #pragma unroll
;     for (int j = 0; j < 8; ++j) s += (v[j].x * v[j].x + v[j].y * v[j].y) + (v[j].z * v[j].z + v[j].w * v[j].w);
;     return 1.0f / sqrtf(wave_sum(s) * (1.f / DM) + EPS);
; }
; __global__ void __launch_bounds__(512, 2) fwd_megakernel(Args args) {
;     ...
;     if (IN(6)) { int t_b = threadIdx.x; asm volatile("" : "+v"(t_b)); const int lane = t_b & 63; int m = gw; f32x4 cur[8]; if (m < NTOK) rms_load(args.out + (size_t)m * DM, lane, cur);
;         for (; m < NTOK; m += NGW) { const int mn = m + NGW; f32x4 nxt[8]; if (mn < NTOK) rms_load(args.out + (size_t)mn * DM, lane, nxt);
;             rms_store_bf16(cur, args.in[10], XN + (size_t)m * DM, lane);
; #pragma unroll
;             for (int j = 0; j < 8; ++j) cur[j] = nxt[j]; } }
.Lp6_body:
	v_pk_mul_f32 v[92:93], v[60:61], v[60:61]
	v_pk_mul_f32 v[94:95], v[56:57], v[56:57]
	v_pk_mul_f32 v[88:89], v[62:63], v[62:63]
	v_pk_mul_f32 v[90:91], v[58:59], v[58:59]
	v_mov_b32_e32 v96, v92
	v_mov_b32_e32 v97, v94
	v_mov_b32_e32 v94, v93
	v_pk_mul_f32 v[84:85], v[54:55], v[54:55]
	v_pk_mul_f32 v[86:87], v[52:53], v[52:53]
	v_pk_add_f32 v[92:93], v[96:97], v[94:95]
	v_mov_b32_e32 v94, v88
	v_mov_b32_e32 v95, v90
	v_mov_b32_e32 v90, v89
	v_pk_add_f32 v[88:89], v[94:95], v[90:91]
	v_pk_mov_b32 v[90:91], v[86:87], v[84:85] op_sel:[1,0]
	v_mov_b32_e32 v87, v85
	v_pk_add_f32 v[84:85], v[90:91], v[86:87]
	v_pk_add_f32 v[88:89], v[92:93], v[88:89]
	v_pk_add_f32 v[84:85], v[84:85], v[84:85] op_sel_hi:[0,1]
	v_mul_f32_e32 v84, v48, v48
	v_pk_fma_f32 v[86:87], v[48:49], v[48:49], v[84:85] op_sel_hi:[1,1,0]
	v_mul_f32_e32 v84, v50, v50
	v_pk_add_f32 v[88:89], v[88:89], v[88:89] op_sel_hi:[0,1]
	v_pk_fma_f32 v[90:91], v[50:51], v[50:51], v[84:85] op_sel_hi:[1,1,0]
	v_mul_f32_e32 v86, v44, v44
	v_mul_f32_e32 v90, v45, v45
	v_mul_f32_e32 v84, v46, v46
	v_mul_f32_e32 v88, v47, v47
	v_pk_mul_f32 v[80:81], v[42:43], v[42:43]
	v_pk_mul_f32 v[82:83], v[40:41], v[40:41]
	v_pk_add_f32 v[86:87], v[86:87], v[90:91]
	v_pk_add_f32 v[84:85], v[84:85], v[88:89]
	v_lshl_add_u64 v[76:77], v[76:77], 0, s[8:9]
	v_pk_add_f32 v[84:85], v[86:87], v[84:85]
	v_pk_mov_b32 v[86:87], v[82:83], v[80:81] op_sel:[1,0]
	v_mov_b32_e32 v83, v81
	v_pk_add_f32 v[80:81], v[86:87], v[82:83]
	v_pk_add_f32 v[84:85], v[84:85], v[84:85] op_sel_hi:[0,1]
	v_pk_add_f32 v[86:87], v[80:81], v[80:81] op_sel_hi:[0,1]
	v_mul_f32_e32 v80, v36, v36
	v_pk_fma_f32 v[88:89], v[36:37], v[36:37], v[80:81] op_sel_hi:[1,1,0]
	v_mul_f32_e32 v80, v38, v38
	v_pk_fma_f32 v[90:91], v[38:39], v[38:39], v[80:81] op_sel_hi:[1,1,0]
	v_mul_f32_e32 v88, v0, v0
	v_mul_f32_e32 v90, v1, v1
	v_mul_f32_e32 v86, v2, v2
	v_mul_f32_e32 v84, v3, v3
	v_pk_add_f32 v[88:89], v[88:89], v[90:91]
	v_pk_add_f32 v[84:85], v[86:87], v[84:85]
	s_nop 0
	v_pk_add_f32 v[84:85], v[88:89], v[84:85]
	s_nop 0
	v_add_f32_e32 v84, v84, v85
	ds_bpermute_b32 v85, v246, v84
	s_waitcnt lgkmcnt(0)
	v_add_f32_e32 v84, v84, v85
	ds_bpermute_b32 v85, v247, v84
	s_waitcnt lgkmcnt(0)
	v_add_f32_e32 v84, v84, v85
	ds_bpermute_b32 v85, v248, v84
	s_waitcnt lgkmcnt(0)
	v_add_f32_e32 v84, v84, v85
	ds_bpermute_b32 v85, v249, v84
	s_waitcnt lgkmcnt(0)
	v_add_f32_e32 v84, v84, v85
	ds_bpermute_b32 v85, v250, v84
	s_waitcnt lgkmcnt(0)
	v_add_f32_e32 v84, v84, v85
	ds_bpermute_b32 v85, v251, v84
	s_waitcnt lgkmcnt(0)
; __device__ __forceinline__ unsigned cvtpk(float lo, float hi) { return pg8::cvt_pk_bf16(lo, hi); }
; __device__ __forceinline__ void rms_store_bf16(const f32x4 (&v)[8], const float* g, bf16* orow, int lane) {
;     const float rstd = rms_rstd(v); const f32x4* gr = (const f32x4*)g + lane; v2u* o8 = (v2u*)orow + lane;
; #pragma unroll
;     for (int j = 0; j < 8; ++j) { const f32x4 gg = gr[64 * j]; v2u w; w.x = cvtpk(v[j].x * rstd * gg.x, v[j].y * rstd * gg.y); w.y = cvtpk(v[j].z * rstd * gg.z, v[j].w * rstd * gg.w); o8[64 * j] = w; }
; }
; __global__ void __launch_bounds__(512, 2) fwd_megakernel(Args args) {
;     ...
;     if (IN(6)) { int t_b = threadIdx.x; asm volatile("" : "+v"(t_b)); const int lane = t_b & 63; int m = gw; f32x4 cur[8]; if (m < NTOK) rms_load(args.out + (size_t)m * DM, lane, cur);
;         for (; m < NTOK; m += NGW) { const int mn = m + NGW; f32x4 nxt[8]; if (mn < NTOK) rms_load(args.out + (size_t)mn * DM, lane, nxt);
;             rms_store_bf16(cur, args.in[10], XN + (size_t)m * DM, lane);
; #pragma unroll
;             for (int j = 0; j < 8; ++j) cur[j] = nxt[j]; } }
	v_add_f32_e32 v84, v84, v85
	v_fmamk_f32 v84, v84, 0x3a000000, v78
	v_mul_f32_e32 v85, 0x4f800000, v84
	v_cmp_gt_f32_e32 vcc, s3, v84
	s_nop 1
	v_cndmask_b32_e32 v84, v84, v85, vcc
	v_sqrt_f32_e32 v85, v84
	s_nop 0
	v_add_u32_e32 v86, -1, v85
	v_fma_f32 v87, -v86, v85, v84
	v_cmp_ge_f32_e64 s[4:5], 0, v87
	v_add_u32_e32 v87, 1, v85
	s_nop 0
	v_cndmask_b32_e64 v86, v85, v86, s[4:5]
	v_fma_f32 v85, -v87, v85, v84
	v_cmp_lt_f32_e64 s[4:5], 0, v85
	s_nop 1
	v_cndmask_b32_e64 v85, v86, v87, s[4:5]
	v_mul_f32_e32 v86, 0x37800000, v85
	v_cndmask_b32_e32 v85, v85, v86, vcc
	v_cmp_class_f32_e32 vcc, v84, v79
	s_nop 1
	v_cndmask_b32_e32 v84, v85, v84, vcc
	v_div_scale_f32 v85, s[4:5], v84, v84, 1.0
	v_rcp_f32_e32 v86, v85
	s_nop 0
	v_fma_f32 v87, -v85, v86, 1.0
	v_fmac_f32_e32 v86, v87, v86
	v_div_scale_f32 v87, vcc, 1.0, v84, 1.0
	v_mul_f32_e32 v88, v87, v86
	v_fma_f32 v89, -v85, v88, v87
	v_fmac_f32_e32 v88, v89, v86
	v_fma_f32 v85, -v85, v88, v87
	v_div_fmas_f32 v85, v85, v86, v88
	v_div_fixup_f32 v84, v85, v84, 1.0
	v_pk_mul_f32 v[60:61], v[60:61], v[84:85] op_sel_hi:[1,0]
	v_pk_mul_f32 v[62:63], v[62:63], v[84:85] op_sel_hi:[1,0]
	v_pk_mul_f32 v[60:61], v[100:101], v[60:61]
	v_pk_mul_f32 v[62:63], v[102:103], v[62:63]
	v_cvt_pk_bf16_f32 v60, v60, v61
	v_cvt_pk_bf16_f32 v61, v62, v63
	global_store_dwordx2 v[74:75], v[60:61], off offset:-3584
	v_pk_mul_f32 v[56:57], v[56:57], v[84:85] op_sel_hi:[1,0]
	v_pk_mul_f32 v[58:59], v[58:59], v[84:85] op_sel_hi:[1,0]
	v_pk_mul_f32 v[52:53], v[52:53], v[84:85] op_sel_hi:[1,0]
	v_pk_mul_f32 v[54:55], v[54:55], v[84:85] op_sel_hi:[1,0]
	v_pk_mul_f32 v[48:49], v[48:49], v[84:85] op_sel_hi:[1,0]
	v_pk_mul_f32 v[50:51], v[50:51], v[84:85] op_sel_hi:[1,0]
	v_pk_mul_f32 v[44:45], v[44:45], v[84:85] op_sel_hi:[1,0]
	v_pk_mul_f32 v[46:47], v[46:47], v[84:85] op_sel_hi:[1,0]
	v_pk_mul_f32 v[40:41], v[40:41], v[84:85] op_sel_hi:[1,0]
	v_pk_mul_f32 v[42:43], v[42:43], v[84:85] op_sel_hi:[1,0]
	v_pk_mul_f32 v[36:37], v[36:37], v[84:85] op_sel_hi:[1,0]
	v_pk_mul_f32 v[38:39], v[38:39], v[84:85] op_sel_hi:[1,0]
	v_pk_mul_f32 v[86:87], v[0:1], v[84:85] op_sel_hi:[1,0]
	v_pk_mul_f32 v[84:85], v[2:3], v[84:85] op_sel_hi:[1,0]
	s_andn2_b64 vcc, exec, s[10:11]
	s_waitcnt vmcnt(0)
	v_mov_b32_e32 v0, v4
	v_mov_b32_e32 v1, v5
	v_mov_b32_e32 v2, v6
	v_mov_b32_e32 v3, v7
	v_pk_mul_f32 v[56:57], v[104:105], v[56:57]
	v_pk_mul_f32 v[58:59], v[106:107], v[58:59]
	v_cvt_pk_bf16_f32 v56, v56, v57
	v_cvt_pk_bf16_f32 v57, v58, v59
	global_store_dwordx2 v[74:75], v[56:57], off offset:-3072
	v_mov_b32_e32 v60, v32
	v_mov_b32_e32 v61, v33
	v_mov_b32_e32 v62, v34
	v_mov_b32_e32 v63, v35
	v_pk_mul_f32 v[52:53], v[108:109], v[52:53]
	v_pk_mul_f32 v[54:55], v[110:111], v[54:55]
	v_cvt_pk_bf16_f32 v52, v52, v53
	v_cvt_pk_bf16_f32 v53, v54, v55
	global_store_dwordx2 v[74:75], v[52:53], off offset:-2560
	v_mov_b32_e32 v56, v28
	v_mov_b32_e32 v57, v29
	v_mov_b32_e32 v58, v30
	v_mov_b32_e32 v59, v31
	v_pk_mul_f32 v[48:49], v[48:49], v[112:113]
	v_pk_mul_f32 v[50:51], v[50:51], v[114:115]
	v_cvt_pk_bf16_f32 v48, v48, v49
	v_cvt_pk_bf16_f32 v49, v50, v51
	global_store_dwordx2 v[74:75], v[48:49], off offset:-2048
	v_mov_b32_e32 v52, v24
	v_mov_b32_e32 v53, v25
	v_mov_b32_e32 v54, v26
	v_mov_b32_e32 v55, v27
	v_pk_mul_f32 v[44:45], v[44:45], v[116:117]
	v_pk_mul_f32 v[46:47], v[46:47], v[118:119]
	v_cvt_pk_bf16_f32 v44, v44, v45
	v_cvt_pk_bf16_f32 v45, v46, v47
	global_store_dwordx2 v[74:75], v[44:45], off offset:-1536
	v_mov_b32_e32 v48, v20
	v_mov_b32_e32 v49, v21
	v_mov_b32_e32 v50, v22
	v_mov_b32_e32 v51, v23
	v_pk_mul_f32 v[40:41], v[40:41], v[120:121]
	v_pk_mul_f32 v[42:43], v[42:43], v[122:123]
	v_cvt_pk_bf16_f32 v40, v40, v41
	v_cvt_pk_bf16_f32 v41, v42, v43
	global_store_dwordx2 v[74:75], v[40:41], off offset:-1024
	v_mov_b32_e32 v44, v16
	v_mov_b32_e32 v45, v17
	v_mov_b32_e32 v46, v18
	v_mov_b32_e32 v47, v19
	v_pk_mul_f32 v[36:37], v[36:37], v[124:125]
	v_pk_mul_f32 v[38:39], v[38:39], v[126:127]
	v_cvt_pk_bf16_f32 v36, v36, v37
	v_cvt_pk_bf16_f32 v37, v38, v39
	global_store_dwordx2 v[74:75], v[36:37], off offset:-512
	v_mov_b32_e32 v40, v12
	v_mov_b32_e32 v41, v13
	v_mov_b32_e32 v42, v14
	v_mov_b32_e32 v43, v15
	v_mov_b32_e32 v36, v8
	v_mov_b32_e32 v37, v9
	v_mov_b32_e32 v38, v10
	v_mov_b32_e32 v39, v11
	v_pk_mul_f32 v[80:81], v[86:87], v[128:129]
	v_pk_mul_f32 v[82:83], v[84:85], v[130:131]
	v_cvt_pk_bf16_f32 v80, v80, v81
	v_cvt_pk_bf16_f32 v81, v82, v83
	global_store_dwordx2 v[74:75], v[80:81], off
	v_lshl_add_u64 v[74:75], v[74:75], 0, s[6:7]
	s_cbranch_vccz .LBB0_626

; __device__ __forceinline__ void rms_load(const float* xrow, int lane, f32x4 (&v)[8]) {
;     const f32x4* xr = (const f32x4*)xrow + lane;
; #pragma unroll
;     for (int j = 0; j < 8; ++j) v[j] = xr[64 * j];
; }
; __global__ void __launch_bounds__(512, 2) fwd_megakernel(Args args) {
;     ...
;     if (IN(11)) { int t_c = threadIdx.x; asm volatile("" : "+v"(t_c)); const int lane = t_c & 63; int m = gw; f32x4 cur[8]; if (m < NTOK) rms_load(args.out + (size_t)m * DM, lane, cur);
;         for (; m < NTOK; m += NGW) { const int mn = m + NGW; f32x4 nxt[8]; if (mn < NTOK) rms_load(args.out + (size_t)mn * DM, lane, nxt);
;             rms_store_f32(cur, args.in[13], args.out + (size_t)m * DM, lane);
; #pragma unroll
;             for (int j = 0; j < 8; ++j) cur[j] = nxt[j]; } }
.LBB0_842:
	s_cmp_lt_i32 s58, 12
	s_cselect_b64 s[0:1], -1, 0
	s_cmp_gt_i32 s59, 11
	s_cselect_b64 s[2:3], -1, 0
	s_and_b64 s[0:1], s[0:1], s[2:3]
	s_and_b64 vcc, exec, s[0:1]
	v_readlane_b32 s12, v255, 2
	v_readlane_b32 s13, v255, 3
	s_cbranch_vccz .LBB0_848
	s_cmpk_gt_i32 s12, 0x5fff
	s_cbranch_scc1 .LBB0_848
	s_ashr_i32 s13, s12, 31
	s_lshl_b64 s[0:1], s[12:13], 13
	v_and_b32_e32 v0, 63, v252
	s_add_u32 s2, s48, s0
	s_addc_u32 s3, s49, s1
	v_lshlrev_b32_e32 v64, 4, v0
	v_mov_b32_e32 v65, 0
	v_lshl_add_u64 v[0:1], s[2:3], 0, v[64:65]
	s_movk_i32 s10, 0x1000
	v_add_co_u32_e32 v8, vcc, s10, v0
	global_load_dwordx4 v[60:63], v64, s[2:3]
	global_load_dwordx4 v[56:59], v64, s[2:3] offset:1024
	global_load_dwordx4 v[52:55], v64, s[2:3] offset:2048
	global_load_dwordx4 v[48:51], v64, s[2:3] offset:3072
	v_addc_co_u32_e32 v9, vcc, 0, v1, vcc
	global_load_dwordx4 v[44:47], v[8:9], off
	global_load_dwordx4 v[40:43], v[8:9], off offset:1024
	global_load_dwordx4 v[4:7], v[8:9], off offset:2048
	global_load_dwordx4 v[0:3], v[8:9], off offset:3072
	v_lshl_add_u64 v[66:67], s[46:47], 0, v[64:65]
	s_mov_b64 s[0:1], 0x1000
	v_lshl_add_u64 v[68:69], v[66:67], 0, s[0:1]
	s_mov_b64 s[0:1], 0x1400
	v_lshl_add_u64 v[70:71], v[66:67], 0, s[0:1]
	s_mov_b64 s[0:1], 0x1800
	v_lshl_add_u64 v[72:73], v[66:67], 0, s[0:1]
	s_mov_b64 s[0:1], 0x1c00
	v_lshl_add_u64 v[74:75], v[66:67], 0, s[0:1]
	s_add_i32 s0, s12, s52
	s_ashr_i32 s53, s52, 31
	s_ashr_i32 s1, s0, 31
	s_lshl_b64 s[4:5], s[52:53], 13
	s_lshl_b64 s[0:1], s[0:1], 13
	s_add_u32 s6, s48, s0
	s_addc_u32 s7, s49, s1
	v_mov_b32_e32 v76, 0x358637bd
	s_mov_b32 s11, 0xf800000
	v_mov_b32_e32 v77, 0x260
	global_load_dwordx4 v[100:103], v[66:67], off
	global_load_dwordx4 v[104:107], v[66:67], off offset:1024
	global_load_dwordx4 v[108:111], v[66:67], off offset:2048
	global_load_dwordx4 v[112:115], v[66:67], off offset:3072
	global_load_dwordx4 v[116:119], v[68:69], off
	global_load_dwordx4 v[120:123], v[70:71], off
	global_load_dwordx4 v[124:127], v[72:73], off
	global_load_dwordx4 v[128:131], v[74:75], off
	s_branch .LBB0_846

; __device__ __forceinline__ void rms_store_f32(const f32x4 (&v)[8], const float* g, float* orow, int lane) {
;     const float rstd = rms_rstd(v); const f32x4* gr = (const f32x4*)g + lane; f32x4* o = (f32x4*)orow + lane;
; #pragma unroll
;     for (int j = 0; j < 8; ++j) { const f32x4 gg = gr[64 * j]; o[64 * j] = v[j] * rstd * gg; }
; }
; __global__ void __launch_bounds__(512, 2) fwd_megakernel(Args args) {
;     ...
;     if (IN(11)) { int t_c = threadIdx.x; asm volatile("" : "+v"(t_c)); const int lane = t_c & 63; int m = gw; f32x4 cur[8]; if (m < NTOK) rms_load(args.out + (size_t)m * DM, lane, cur);
;         for (; m < NTOK; m += NGW) { const int mn = m + NGW; f32x4 nxt[8]; if (mn < NTOK) rms_load(args.out + (size_t)mn * DM, lane, nxt);
;             rms_store_f32(cur, args.in[13], args.out + (size_t)m * DM, lane);
; #pragma unroll
;             for (int j = 0; j < 8; ++j) cur[j] = nxt[j]; } }
.Lp11_body:
	v_mov_b32_e32 v80, v61
	v_mov_b32_e32 v81, v57
	v_mov_b32_e32 v78, v60
	v_mov_b32_e32 v79, v56
	v_pk_mul_f32 v[80:81], v[80:81], v[80:81]
	v_mov_b32_e32 v82, v63
	v_mov_b32_e32 v83, v59
	v_pk_fma_f32 v[78:79], v[78:79], v[78:79], v[80:81]
	v_mov_b32_e32 v80, v62
	v_mov_b32_e32 v81, v58
	v_pk_mul_f32 v[82:83], v[82:83], v[82:83]
	v_mul_f32_e32 v86, v2, v2
	v_pk_fma_f32 v[80:81], v[80:81], v[80:81], v[82:83]
	v_pk_mul_f32 v[82:83], v[52:53], v[52:53]
	v_pk_add_f32 v[78:79], v[78:79], v[80:81]
	v_pk_mul_f32 v[80:81], v[54:55], v[54:55]
	v_pk_add_f32 v[78:79], v[78:79], v[78:79] op_sel:[0,1] op_sel_hi:[1,0]
	v_pk_mov_b32 v[84:85], v[82:83], v[80:81] op_sel:[1,0]
	v_mov_b32_e32 v83, v81
	v_pk_add_f32 v[80:81], v[84:85], v[82:83]
	v_mul_f32_e32 v82, v44, v44
	v_mul_f32_e32 v83, v45, v45
	v_pk_add_f32 v[80:81], v[80:81], v[80:81] op_sel:[0,1] op_sel_hi:[1,0]
	v_mov_b32_e32 v79, v82
	v_mov_b32_e32 v81, v83
	v_pk_add_f32 v[78:79], v[78:79], v[80:81]
	v_mul_f32_e32 v80, v49, v49
	v_mul_f32_e32 v82, v51, v51
	v_mul_f32_e32 v84, v46, v46
	v_mul_f32_e32 v85, v47, v47
	v_pk_fma_f32 v[80:81], v[48:49], v[48:49], v[80:81] op_sel_hi:[1,1,0]
	v_pk_fma_f32 v[82:83], v[50:51], v[50:51], v[82:83] op_sel_hi:[1,1,0]
	v_mov_b32_e32 v81, v84
	v_mov_b32_e32 v83, v85
	v_pk_add_f32 v[80:81], v[80:81], v[82:83]
	v_pk_mul_f32 v[82:83], v[40:41], v[40:41]
	v_pk_add_f32 v[78:79], v[78:79], v[80:81]
	v_pk_mul_f32 v[80:81], v[42:43], v[42:43]
	v_pk_add_f32 v[78:79], v[78:79], v[78:79] op_sel:[0,1] op_sel_hi:[1,0]
	v_pk_mov_b32 v[84:85], v[82:83], v[80:81] op_sel:[1,0]
	v_mov_b32_e32 v83, v81
	v_pk_add_f32 v[80:81], v[84:85], v[82:83]
	v_mul_f32_e32 v82, v0, v0
	v_mul_f32_e32 v83, v1, v1
	v_pk_add_f32 v[80:81], v[80:81], v[80:81] op_sel:[0,1] op_sel_hi:[1,0]
	v_mov_b32_e32 v79, v82
	v_mov_b32_e32 v81, v83
	v_pk_add_f32 v[82:83], v[78:79], v[80:81]
	v_mul_f32_e32 v78, v5, v5
	v_pk_fma_f32 v[84:85], v[4:5], v[4:5], v[78:79] op_sel_hi:[1,1,0]
	v_mul_f32_e32 v78, v7, v7
	v_mov_b32_e32 v85, v86
	v_pk_fma_f32 v[86:87], v[6:7], v[6:7], v[78:79] op_sel_hi:[1,1,0]
	v_mul_f32_e32 v88, v3, v3
	v_mov_b32_e32 v87, v88
	v_pk_add_f32 v[84:85], v[84:85], v[86:87]
	s_nop 0
	v_pk_add_f32 v[82:83], v[82:83], v[84:85]
	s_nop 0
	v_add_f32_e32 v82, v82, v83
	ds_bpermute_b32 v83, v246, v82
	s_waitcnt lgkmcnt(0)
	v_add_f32_e32 v82, v82, v83
	ds_bpermute_b32 v83, v247, v82
	s_waitcnt lgkmcnt(0)
	v_add_f32_e32 v82, v82, v83
	ds_bpermute_b32 v83, v248, v82
	s_waitcnt lgkmcnt(0)
	v_add_f32_e32 v82, v82, v83
	ds_bpermute_b32 v83, v249, v82
	s_waitcnt lgkmcnt(0)
	v_add_f32_e32 v82, v82, v83
	ds_bpermute_b32 v83, v250, v82
	s_waitcnt lgkmcnt(0)
	v_add_f32_e32 v82, v82, v83
	ds_bpermute_b32 v83, v251, v82
	s_waitcnt lgkmcnt(0)
	v_add_f32_e32 v82, v82, v83
	v_fmamk_f32 v82, v82, 0x3a000000, v76
	v_mul_f32_e32 v83, 0x4f800000, v82
	v_cmp_gt_f32_e32 vcc, s11, v82
	s_nop 1
	v_cndmask_b32_e32 v82, v82, v83, vcc
	v_sqrt_f32_e32 v83, v82
	s_nop 0
	v_add_u32_e32 v84, -1, v83
	v_fma_f32 v85, -v84, v83, v82
	v_cmp_ge_f32_e64 s[0:1], 0, v85
	v_add_u32_e32 v85, 1, v83
	s_nop 0
	v_cndmask_b32_e64 v84, v83, v84, s[0:1]
	v_fma_f32 v83, -v85, v83, v82
	v_cmp_lt_f32_e64 s[0:1], 0, v83
	s_nop 1
	v_cndmask_b32_e64 v83, v84, v85, s[0:1]
	v_mul_f32_e32 v84, 0x37800000, v83
	v_cndmask_b32_e32 v83, v83, v84, vcc
	v_cmp_class_f32_e32 vcc, v82, v77
	s_nop 1
	v_cndmask_b32_e32 v82, v83, v82, vcc
	v_div_scale_f32 v83, s[0:1], v82, v82, 1.0
	v_rcp_f32_e32 v84, v83
	s_nop 0
	v_fma_f32 v85, -v83, v84, 1.0
	v_fmac_f32_e32 v84, v85, v84
	v_div_scale_f32 v85, vcc, 1.0, v82, 1.0
	v_mul_f32_e32 v86, v85, v84
	v_fma_f32 v87, -v83, v86, v85
	v_fmac_f32_e32 v86, v87, v84
	v_fma_f32 v83, -v83, v86, v85
	v_div_fmas_f32 v83, v83, v84, v86
	v_div_fixup_f32 v82, v83, v82, 1.0
	v_pk_mul_f32 v[60:61], v[60:61], v[82:83] op_sel_hi:[1,0]
	v_pk_mul_f32 v[62:63], v[62:63], v[82:83] op_sel_hi:[1,0]
	v_lshl_add_u64 v[84:85], s[2:3], 0, v[64:65]
	v_pk_mul_f32 v[62:63], v[102:103], v[62:63]
	v_pk_mul_f32 v[60:61], v[100:101], v[60:61]
	global_store_dwordx4 v[84:85], v[60:63], off
	s_nop 0
	v_pk_mul_f32 v[58:59], v[58:59], v[82:83] op_sel_hi:[1,0]
	v_pk_mul_f32 v[56:57], v[56:57], v[82:83] op_sel_hi:[1,0]
	v_pk_mul_f32 v[54:55], v[54:55], v[82:83] op_sel_hi:[1,0]
	v_pk_mul_f32 v[52:53], v[52:53], v[82:83] op_sel_hi:[1,0]
	v_pk_mul_f32 v[50:51], v[50:51], v[82:83] op_sel_hi:[1,0]
	v_pk_mul_f32 v[48:49], v[48:49], v[82:83] op_sel_hi:[1,0]
	v_add_co_u32_e32 v78, vcc, s10, v84
	v_pk_mul_f32 v[46:47], v[46:47], v[82:83] op_sel_hi:[1,0]
	v_pk_mul_f32 v[44:45], v[44:45], v[82:83] op_sel_hi:[1,0]
	v_addc_co_u32_e32 v79, vcc, 0, v85, vcc
	v_pk_mul_f32 v[42:43], v[42:43], v[82:83] op_sel_hi:[1,0]
	v_pk_mul_f32 v[40:41], v[40:41], v[82:83] op_sel_hi:[1,0]
	v_pk_mul_f32 v[6:7], v[6:7], v[82:83] op_sel_hi:[1,0]
	v_pk_mul_f32 v[4:5], v[4:5], v[82:83] op_sel_hi:[1,0]
	s_add_u32 s2, s2, s4
	v_pk_mul_f32 v[80:81], v[2:3], v[82:83] op_sel_hi:[1,0]
	v_pk_mul_f32 v[82:83], v[0:1], v[82:83] op_sel_hi:[1,0]
	s_addc_u32 s3, s3, s5
	s_add_u32 s6, s6, s4
	s_waitcnt vmcnt(0)
	v_mov_b64_e32 v[0:1], v[24:25]
	s_addc_u32 s7, s7, s5
	s_andn2_b64 vcc, exec, s[8:9]
	v_mov_b64_e32 v[2:3], v[26:27]
	v_pk_mul_f32 v[56:57], v[104:105], v[56:57]
	v_pk_mul_f32 v[58:59], v[106:107], v[58:59]
	global_store_dwordx4 v[84:85], v[56:59], off offset:1024
	s_nop 0
	v_pk_mul_f32 v[52:53], v[108:109], v[52:53]
	v_pk_mul_f32 v[54:55], v[110:111], v[54:55]
	global_store_dwordx4 v[84:85], v[52:55], off offset:2048
	s_nop 0
	v_mov_b64_e32 v[58:59], v[18:19]
	v_mov_b64_e32 v[56:57], v[16:17]
	v_pk_mul_f32 v[48:49], v[112:113], v[48:49]
	v_pk_mul_f32 v[50:51], v[114:115], v[50:51]
	global_store_dwordx4 v[84:85], v[48:51], off offset:3072
	s_nop 0
	v_mov_b64_e32 v[54:55], v[14:15]
	v_mov_b64_e32 v[52:53], v[12:13]
	v_pk_mul_f32 v[44:45], v[116:117], v[44:45]
	v_pk_mul_f32 v[46:47], v[118:119], v[46:47]
	global_store_dwordx4 v[78:79], v[44:47], off
	s_nop 0
	v_mov_b64_e32 v[50:51], v[10:11]
	v_mov_b64_e32 v[48:49], v[8:9]
	v_pk_mul_f32 v[40:41], v[40:41], v[120:121]
	v_pk_mul_f32 v[42:43], v[42:43], v[122:123]
	global_store_dwordx4 v[78:79], v[40:43], off offset:1024
	s_nop 0
	v_mov_b64_e32 v[46:47], v[38:39]
	v_mov_b64_e32 v[44:45], v[36:37]
	v_pk_mul_f32 v[4:5], v[4:5], v[124:125]
	v_pk_mul_f32 v[6:7], v[6:7], v[126:127]
	global_store_dwordx4 v[78:79], v[4:7], off offset:2048
	s_nop 0
	v_mov_b64_e32 v[42:43], v[34:35]
	v_mov_b64_e32 v[4:5], v[28:29]
	v_mov_b64_e32 v[6:7], v[30:31]
	v_mov_b64_e32 v[40:41], v[32:33]
	v_pk_mul_f32 v[60:61], v[82:83], v[128:129]
	v_pk_mul_f32 v[62:63], v[80:81], v[130:131]
	global_store_dwordx4 v[78:79], v[60:63], off offset:3072
	s_nop 1
	v_mov_b64_e32 v[62:63], v[22:23]
	v_mov_b64_e32 v[60:61], v[20:21]
	s_cbranch_vccz .LBB0_848
; __global__ void __launch_bounds__(512, 2) fwd_megakernel(Args args) {
;     ...
;     if (IN(11)) { int t_c = threadIdx.x; asm volatile("" : "+v"(t_c)); const int lane = t_c & 63; int m = gw; f32x4 cur[8]; if (m < NTOK) rms_load(args.out + (size_t)m * DM, lane, cur);
;         for (; m < NTOK; m += NGW) { const int mn = m + NGW; f32x4 nxt[8]; if (mn < NTOK) rms_load(args.out + (size_t)mn * DM, lane, nxt);
;             rms_store_f32(cur, args.in[13], args.out + (size_t)m * DM, lane);
; #pragma unroll
;             for (int j = 0; j < 8; ++j) cur[j] = nxt[j]; } }
.LBB0_846:
	s_add_i32 s12, s12, s52
	s_cmpk_gt_i32 s12, 0x5fff
	s_cselect_b64 s[8:9], -1, 0
	s_and_b64 vcc, exec, s[8:9]
	s_cbranch_vccnz .Lp11_nonext
	v_lshl_add_u64 v[24:25], s[6:7], 0, v[64:65]
	v_add_co_u32_e32 v78, vcc, 0x1000, v24
	global_load_dwordx4 v[20:23], v[24:25], off
	global_load_dwordx4 v[16:19], v[24:25], off offset:1024
	global_load_dwordx4 v[12:15], v[24:25], off offset:2048
	global_load_dwordx4 v[8:11], v[24:25], off offset:3072
	v_addc_co_u32_e32 v79, vcc, 0, v25, vcc
	global_load_dwordx4 v[36:39], v[78:79], off
	global_load_dwordx4 v[32:35], v[78:79], off offset:1024
	global_load_dwordx4 v[28:31], v[78:79], off offset:2048
	global_load_dwordx4 v[24:27], v[78:79], off offset:3072
	s_branch .LBB0_845
.Lp11_nonext:
	s_waitcnt vmcnt(0)
	s_branch .Lp11_body
.LBB0_848:
	s_endpgm
